# accumulate-chain MFMA order also in attention (QK 4-chains, PV 2-chains)
# baseline (speedup 1.0000x reference)
.LBB0_235:
	v_sub_f32_e32 v80, v80, v145
	v_exp_f32_e32 v80, v80
	v_sub_f32_e32 v81, v81, v145
	v_exp_f32_e32 v81, v81
	v_sub_f32_e32 v82, v82, v145
	v_exp_f32_e32 v82, v82
	v_sub_f32_e32 v83, v83, v145
	v_exp_f32_e32 v83, v83
	v_sub_f32_e32 v84, v84, v145
	v_add_f32_e32 v188, 0, v80
	v_exp_f32_e32 v84, v84
	v_sub_f32_e32 v85, v85, v145
	v_add_f32_e32 v188, v81, v188
	v_exp_f32_e32 v85, v85
	v_sub_f32_e32 v86, v86, v145
	v_add_f32_e32 v188, v82, v188
	v_exp_f32_e32 v86, v86
	v_sub_f32_e32 v87, v87, v145
	v_add_f32_e32 v188, v83, v188
	v_exp_f32_e32 v87, v87
	v_sub_f32_e32 v88, v88, v145
	v_add_f32_e32 v188, v84, v188
	v_exp_f32_e32 v88, v88
	v_sub_f32_e32 v89, v89, v145
	v_add_f32_e32 v188, v85, v188
	v_exp_f32_e32 v89, v89
	v_sub_f32_e32 v90, v90, v145
	v_add_f32_e32 v188, v86, v188
	v_exp_f32_e32 v90, v90
	v_sub_f32_e32 v91, v91, v145
	v_add_f32_e32 v188, v87, v188
	v_exp_f32_e32 v91, v91
	v_sub_f32_e32 v92, v92, v145
	v_add_f32_e32 v188, v88, v188
	v_exp_f32_e32 v92, v92
	v_sub_f32_e32 v93, v93, v145
	v_add_f32_e32 v188, v89, v188
	v_exp_f32_e32 v93, v93
	v_sub_f32_e32 v94, v94, v145
	v_add_f32_e32 v188, v90, v188
	v_exp_f32_e32 v94, v94
	v_sub_f32_e32 v95, v95, v145
	v_add_f32_e32 v188, v91, v188
	v_exp_f32_e32 v95, v95
	v_sub_f32_e32 v64, v64, v145
	v_add_f32_e32 v188, v92, v188
	v_exp_f32_e32 v189, v64
	v_sub_f32_e32 v64, v65, v145
	v_add_f32_e32 v188, v93, v188
	v_exp_f32_e32 v190, v64
	v_sub_f32_e32 v64, v66, v145
	v_add_f32_e32 v188, v94, v188
	v_exp_f32_e32 v191, v64
	v_sub_f32_e32 v64, v67, v145
	v_add_f32_e32 v188, v95, v188
	v_exp_f32_e32 v192, v64
	v_sub_f32_e32 v65, v68, v145
	v_add_f32_e32 v64, v189, v188
	v_exp_f32_e32 v188, v65
	v_sub_f32_e32 v65, v69, v145
	v_add_f32_e32 v64, v190, v64
	v_exp_f32_e32 v193, v65
	v_sub_f32_e32 v65, v70, v145
	v_add_f32_e32 v64, v191, v64
	v_exp_f32_e32 v194, v65
	v_sub_f32_e32 v65, v71, v145
	v_add_f32_e32 v64, v192, v64
	v_exp_f32_e32 v195, v65
	v_sub_f32_e32 v65, v72, v145
	v_add_f32_e32 v64, v188, v64
	v_exp_f32_e32 v196, v65
	v_sub_f32_e32 v65, v73, v145
	v_add_f32_e32 v64, v193, v64
	v_exp_f32_e32 v197, v65
	v_sub_f32_e32 v65, v74, v145
	v_add_f32_e32 v64, v194, v64
	v_exp_f32_e32 v198, v65
	v_sub_f32_e32 v65, v75, v145
	v_add_f32_e32 v64, v195, v64
	v_exp_f32_e32 v199, v65
	v_sub_f32_e32 v65, v76, v145
	v_add_f32_e32 v64, v196, v64
	v_exp_f32_e32 v200, v65
	v_sub_f32_e32 v65, v77, v145
	v_add_f32_e32 v64, v197, v64
	v_exp_f32_e32 v201, v65
	v_sub_f32_e32 v65, v78, v145
	v_add_f32_e32 v64, v198, v64
	v_exp_f32_e32 v202, v65
	v_sub_f32_e32 v65, v79, v145
	v_add_f32_e32 v64, v199, v64
	v_exp_f32_e32 v79, v65
	v_add_f32_e32 v64, v200, v64
	v_add_f32_e32 v64, v201, v64
	v_subrev_u32_e32 v151, s26, v176
	v_subrev_u32_e32 v187, s26, v174
	v_add_f32_e32 v64, v202, v64
	v_add_u32_e32 v204, s54, v181
	v_add_f32_e32 v212, v79, v64
	v_cvt_pk_bf16_f32 v64, v80, v81
	v_cvt_pk_bf16_f32 v65, v82, v83
	v_cvt_pk_bf16_f32 v66, v84, v85
	v_cvt_pk_bf16_f32 v67, v86, v87
	v_cvt_pk_bf16_f32 v68, v88, v89
	v_cvt_pk_bf16_f32 v69, v90, v91
	v_cvt_pk_bf16_f32 v70, v92, v93
	v_add_u32_e32 v92, v204, v187
	v_add_u32_e32 v151, v204, v151
	v_cvt_pk_bf16_f32 v71, v94, v95
	v_cvt_pk_bf16_f32 v72, v189, v190
	v_cvt_pk_bf16_f32 v73, v191, v192
	v_cvt_pk_bf16_f32 v74, v188, v193
	v_cvt_pk_bf16_f32 v75, v194, v195
	v_cvt_pk_bf16_f32 v76, v196, v197
	v_cvt_pk_bf16_f32 v77, v198, v199
	v_cvt_pk_bf16_f32 v78, v200, v201
	v_cvt_pk_bf16_f32 v79, v202, v79
	ds_read_b128 v[80:83], v92 offset:16384
	ds_read_b128 v[84:87], v92 offset:20480
	ds_read_b128 v[88:91], v92 offset:24576
	ds_read_b128 v[92:95], v92 offset:28672
	ds_read_b128 v[188:191], v151 offset:16384
	ds_read_b128 v[192:195], v151 offset:20480
	ds_read_b128 v[196:199], v151 offset:24576
	ds_read_b128 v[200:203], v151 offset:28672
	v_subrev_u32_e32 v147, s26, v180
	v_subrev_u32_e32 v149, s26, v178
	v_add_u32_e32 v149, v204, v149
	v_add_u32_e32 v147, v204, v147
	ds_read_b128 v[208:211], v149 offset:16384
	ds_read_b128 v[214:217], v149 offset:20480
	ds_read_b128 v[230:233], v149 offset:24576
	ds_read_b128 v[234:237], v149 offset:28672
	ds_read_b128 v[238:241], v147 offset:16384
	ds_read_b128 v[242:245], v147 offset:20480
	ds_read_b128 v[246:249], v147 offset:24576
	ds_read_b128 v[204:207], v147 offset:28672
	s_setprio 1
	s_waitcnt lgkmcnt(8)
	v_mfma_f32_32x32x16_bf16 v[48:63], v[80:83], v[64:67], v[48:63]
	v_mfma_f32_32x32x16_bf16 v[48:63], v[188:191], v[68:71], v[48:63]
	v_mfma_f32_32x32x16_bf16 v[32:47], v[84:87], v[64:67], v[32:47]
	v_mfma_f32_32x32x16_bf16 v[32:47], v[192:195], v[68:71], v[32:47]
	v_mfma_f32_32x32x16_bf16 v[16:31], v[88:91], v[64:67], v[16:31]
	v_mfma_f32_32x32x16_bf16 v[16:31], v[196:199], v[68:71], v[16:31]
	v_mfma_f32_32x32x16_bf16 v[0:15], v[92:95], v[64:67], v[0:15]
	v_mfma_f32_32x32x16_bf16 v[0:15], v[200:203], v[68:71], v[0:15]
	s_waitcnt lgkmcnt(0)
	v_mfma_f32_32x32x16_bf16 v[48:63], v[208:211], v[72:75], v[48:63]
	v_add_f32_e32 v143, v143, v212
	v_mfma_f32_32x32x16_bf16 v[48:63], v[238:241], v[76:79], v[48:63]
	v_mfma_f32_32x32x16_bf16 v[32:47], v[214:217], v[72:75], v[32:47]
	v_mfma_f32_32x32x16_bf16 v[32:47], v[242:245], v[76:79], v[32:47]
	v_mfma_f32_32x32x16_bf16 v[16:31], v[230:233], v[72:75], v[16:31]
	v_mfma_f32_32x32x16_bf16 v[16:31], v[246:249], v[76:79], v[16:31]
	v_mfma_f32_32x32x16_bf16 v[0:15], v[234:237], v[72:75], v[0:15]
	v_mfma_f32_32x32x16_bf16 v[0:15], v[204:207], v[76:79], v[0:15]
	s_setprio 0

.LBB0_243:
	s_cmp_gt_i32 s26, s52
	s_cbranch_scc1 .LBB0_236
	s_mul_hi_u32 s26, s55, 0xaaaaaaab
	s_lshr_b32 s26, s26, 1
	s_mul_i32 s26, s26, 0x18000
	v_subrev_u32_e32 v72, s26, v179
	v_subrev_u32_e32 v73, s26, v177
	v_subrev_u32_e32 v74, s26, v175
	v_subrev_u32_e32 v64, s26, v173
	v_add_u32_e32 v75, s54, v182
	v_add_u32_e32 v68, v75, v64
	v_add_u32_e32 v74, v75, v74
	v_add_u32_e32 v73, v75, v73
	v_add_u32_e32 v72, v75, v72
	ds_read_b128 v[64:67], v68
	ds_read_b128 v[68:71], v68 offset:8192
	ds_read_b128 v[188:191], v74
	ds_read_b128 v[192:195], v74 offset:8192
	ds_read_b128 v[196:199], v73
	ds_read_b128 v[200:203], v73 offset:8192
	ds_read_b128 v[208:211], v72
	ds_read_b128 v[214:217], v72 offset:8192
	s_waitcnt lgkmcnt(0)
	s_setprio 1
	s_waitcnt lgkmcnt(0)
	v_mfma_f32_32x32x16_bf16 v[80:95], v[64:67], v[96:99], 0
	v_mfma_f32_32x32x16_bf16 v[80:95], v[188:191], v[100:103], v[80:95]
	v_mfma_f32_32x32x16_bf16 v[80:95], v[196:199], v[104:107], v[80:95]
	v_mfma_f32_32x32x16_bf16 v[80:95], v[208:211], v[108:111], v[80:95]
	v_mfma_f32_32x32x16_bf16 v[64:79], v[68:71], v[96:99], 0
	v_mfma_f32_32x32x16_bf16 v[64:79], v[192:195], v[100:103], v[64:79]
	v_mfma_f32_32x32x16_bf16 v[64:79], v[200:203], v[104:107], v[64:79]
	v_mfma_f32_32x32x16_bf16 v[64:79], v[214:217], v[108:111], v[64:79]
	s_setprio 0
	s_nop 10
	v_max3_f32 v147, v80, v81, v82
	v_max3_f32 v149, v64, v65, v66
	v_max3_f32 v147, v147, v83, v84
	v_max3_f32 v149, v149, v67, v68
	v_max3_f32 v147, v147, v85, v86
	v_max3_f32 v149, v149, v69, v70
	v_max3_f32 v147, v147, v87, v88
	v_max3_f32 v149, v149, v71, v72
	v_max3_f32 v147, v147, v89, v90
	v_max3_f32 v149, v149, v73, v74
	v_max3_f32 v147, v147, v91, v92
	v_max3_f32 v149, v149, v75, v76
	v_max3_f32 v147, v147, v93, v94
	v_max3_f32 v149, v149, v77, v78
	v_max3_f32 v147, v147, v95, v79
	v_max_f32_e32 v147, v147, v149
	v_mov_b32_e32 v149, v147
	s_nop 1
	v_permlane32_swap_b32_e32 v147, v149
	v_max_f32_e32 v149, v149, v149
	v_max_f32_e32 v147, v147, v147
	v_max_f32_e32 v147, v147, v149
	v_cmp_gt_f32_e32 vcc, v147, v145
	s_cbranch_vccz .LBB0_235
	v_max_f32_e32 v147, v147, v147
	v_max_f32_e32 v149, v145, v145
	v_max_f32_e32 v147, v149, v147
	v_sub_f32_e32 v145, v145, v147
	v_exp_f32_e32 v188, v145
	v_mov_b32_e32 v145, v147
	v_pk_mul_f32 v[62:63], v[62:63], v[188:189] op_sel_hi:[1,0]
	v_pk_mul_f32 v[60:61], v[60:61], v[188:189] op_sel_hi:[1,0]
	v_pk_mul_f32 v[58:59], v[58:59], v[188:189] op_sel_hi:[1,0]
	v_pk_mul_f32 v[56:57], v[56:57], v[188:189] op_sel_hi:[1,0]
	v_pk_mul_f32 v[54:55], v[54:55], v[188:189] op_sel_hi:[1,0]
	v_pk_mul_f32 v[52:53], v[52:53], v[188:189] op_sel_hi:[1,0]
	v_pk_mul_f32 v[50:51], v[50:51], v[188:189] op_sel_hi:[1,0]
	v_pk_mul_f32 v[48:49], v[48:49], v[188:189] op_sel_hi:[1,0]
	v_pk_mul_f32 v[46:47], v[46:47], v[188:189] op_sel_hi:[1,0]
	v_pk_mul_f32 v[44:45], v[44:45], v[188:189] op_sel_hi:[1,0]
	v_pk_mul_f32 v[42:43], v[42:43], v[188:189] op_sel_hi:[1,0]
	v_pk_mul_f32 v[40:41], v[40:41], v[188:189] op_sel_hi:[1,0]
	v_pk_mul_f32 v[38:39], v[38:39], v[188:189] op_sel_hi:[1,0]
	v_pk_mul_f32 v[36:37], v[36:37], v[188:189] op_sel_hi:[1,0]
	v_pk_mul_f32 v[34:35], v[34:35], v[188:189] op_sel_hi:[1,0]
	v_pk_mul_f32 v[32:33], v[32:33], v[188:189] op_sel_hi:[1,0]
	v_pk_mul_f32 v[30:31], v[30:31], v[188:189] op_sel_hi:[1,0]
	v_pk_mul_f32 v[28:29], v[28:29], v[188:189] op_sel_hi:[1,0]
	v_pk_mul_f32 v[26:27], v[26:27], v[188:189] op_sel_hi:[1,0]
	v_pk_mul_f32 v[24:25], v[24:25], v[188:189] op_sel_hi:[1,0]
	v_pk_mul_f32 v[22:23], v[22:23], v[188:189] op_sel_hi:[1,0]
	v_pk_mul_f32 v[20:21], v[20:21], v[188:189] op_sel_hi:[1,0]
	v_pk_mul_f32 v[18:19], v[18:19], v[188:189] op_sel_hi:[1,0]
	v_pk_mul_f32 v[16:17], v[16:17], v[188:189] op_sel_hi:[1,0]
	v_pk_mul_f32 v[14:15], v[14:15], v[188:189] op_sel_hi:[1,0]
	v_pk_mul_f32 v[12:13], v[12:13], v[188:189] op_sel_hi:[1,0]
	v_pk_mul_f32 v[10:11], v[10:11], v[188:189] op_sel_hi:[1,0]
	v_pk_mul_f32 v[8:9], v[8:9], v[188:189] op_sel_hi:[1,0]
	v_pk_mul_f32 v[6:7], v[6:7], v[188:189] op_sel_hi:[1,0]
	v_pk_mul_f32 v[4:5], v[4:5], v[188:189] op_sel_hi:[1,0]
	v_pk_mul_f32 v[2:3], v[2:3], v[188:189] op_sel_hi:[1,0]
	v_pk_mul_f32 v[0:1], v[0:1], v[188:189] op_sel_hi:[1,0]
	v_mul_f32_e32 v143, v143, v188
	s_branch .LBB0_235
